# rebalance: 8960 expert-table rows converted in the P3 slack
# baseline (speedup 1.0000x reference)
; __global__ void __launch_bounds__(NTHR, 2) mega(Args args) {
;     ...
;         {
;             const int nslots = G >> 3, rr = 103 % nslots, xcd = (int)blockIdx.x & 7, slot = (int)blockIdx.x >> 3;
;             const bool freewg = rr == 0 || slot >= rr;
;             const int fidx = rr == 0 ? (int)blockIdx.x : (slot - rr) * 8 + xcd, nfree = rr == 0 ? G : (nslots - rr) * 8;
;             if (freewg && rep == 0)
;                 for (int e = fidx * NWAVES + wave; e < 2 * 16384 - CVT_LATE; e += nfree * NWAVES) { if (e < 16384) peer::cvt_row_i4(pu, UT8, SUs, e, lane); else peer::cvt_row_fp4(pv, VT8, SVs, e - 16384, lane); }
.LBB0_458:
	s_ashr_i32 s1, s18, 3
	s_abs_i32 s3, s1
	v_cvt_f32_u32_e32 v1, s3
	s_sub_i32 s4, 0, s3
	s_ashr_i32 s0, s2, 3
	v_rcp_iflag_f32_e32 v1, v1
	s_nop 0
	v_mul_f32_e32 v1, 0x4f7ffffe, v1
	v_cvt_u32_f32_e32 v1, v1
	s_nop 0
	v_readfirstlane_b32 s5, v1
	s_mul_i32 s4, s4, s5
	s_mul_hi_u32 s4, s5, s4
	s_add_i32 s5, s5, s4
	s_mul_hi_u32 s4, s5, 0x67
	s_mul_i32 s4, s4, s3
	s_sub_i32 s4, 0x67, s4
	s_sub_i32 s5, s4, s3
	s_cmp_ge_u32 s4, s3
	s_cselect_b32 s4, s5, s4
	s_sub_i32 s5, s4, s3
	s_cmp_ge_u32 s4, s3
	s_cselect_b32 s6, s5, s4
	s_cmp_eq_u32 s6, 0
	s_cselect_b64 s[4:5], -1, 0
	s_cmp_lg_u32 s6, 0
	s_cselect_b64 s[8:9], -1, 0
	s_cmp_lt_i32 s0, s6
	s_cselect_b64 s[10:11], -1, 0
	s_and_b64 s[8:9], s[8:9], s[10:11]
	s_and_b64 vcc, exec, s[8:9]
	s_cbranch_vccnz .LBB0_472
	s_sub_i32 s0, s0, s6
	s_and_b32 s3, s2, 7
	s_lshl_b32 s0, s0, 3
	s_or_b32 s0, s0, s3
	s_and_b64 s[8:9], s[4:5], exec
	s_cselect_b32 s0, s2, s0
	s_lshl_b32 s3, s0, 3
	s_add_i32 s0, s3, s77
	s_cmpk_gt_i32 s0, 0x5cff
	s_cbranch_scc1 .LBB0_472
	s_sub_i32 s1, s1, s6
	s_lshl_b32 s1, s1, 3
	s_and_b64 s[4:5], s[4:5], exec
	s_cselect_b32 s1, s18, s1
	s_lshl_b32 s10, s1, 3
	s_ashr_i32 s1, s3, 31
	s_add_u32 s34, s77, s3
	v_and_b32_e32 v1, 1, v0
	s_addc_u32 s35, 0, s1
	v_mov_b32_e32 v3, 0
	v_cmp_eq_u32_e64 s[4:5], 0, v1
	v_lshlrev_b32_e32 v1, 10, v0
	s_lshl_b64 s[12:13], s[34:35], 2
	v_and_b32_e32 v6, 0xc000, v1
	v_mov_b32_e32 v7, v3
	s_add_u32 s1, s30, s12
	s_addc_u32 s3, s31, s13
	v_lshl_add_u64 v[10:11], s[34:35], 0, v[6:7]
	v_lshlrev_b32_e32 v1, 3, v0
	s_add_u32 s12, s1, 0x3000000
	v_lshlrev_b64 v[10:11], 7, v[10:11]
	s_movk_i32 s1, 0x78
	v_and_or_b32 v10, v1, s1, v10
	s_addc_u32 s13, s3, 0
	s_ashr_i32 s11, s10, 31
	v_lshl_add_u64 v[10:11], s[30:31], 0, v[10:11]
	s_mov_b64 s[16:17], 0x1000000
	s_lshl_b64 s[14:15], s[10:11], 2
	v_lshl_add_u64 v[10:11], v[10:11], 0, s[16:17]
	s_lshl_b64 s[16:17], s[10:11], 7
	s_lshl_b64 s[34:35], s[34:35], 12
	v_and_b32_e32 v8, 0x70, v1
	s_mov_b64 s[82:83], s[22:23]
	s_add_u32 s22, s22, s34
	v_mbcnt_lo_u32_b32 v1, -1, 0
	v_lshlrev_b32_e32 v2, 6, v178
	s_addc_u32 s23, s23, s35
	v_mbcnt_hi_u32_b32 v1, -1, v1
	v_lshl_add_u64 v[4:5], s[24:25], 0, v[2:3]
	v_mov_b32_e32 v9, v3
	v_lshl_add_u64 v[12:13], s[22:23], 0, v[2:3]
	v_and_b32_e32 v2, 64, v1
	s_mov_b32 s9, 0
	v_lshl_add_u64 v[8:9], s[20:21], 0, v[8:9]
	v_cmp_eq_u32_e64 s[6:7], 0, v178
	v_lshl_add_u64 v[12:13], v[12:13], 0, 32
	s_lshl_b64 s[22:23], s[10:11], 12
	s_mov_b32 s1, 0x40e00000
	s_movk_i32 s3, 0xf0
	s_movk_i32 s11, 0xf00
	s_mov_b32 s19, 0xf0000
	s_mov_b32 s34, 0xf000000
	s_mov_b32 s35, 0xc050c00
	s_mov_b32 s42, 0xf0f0f0f
	s_mov_b32 s43, 0xff00ff
	v_add_u32_e32 v7, 64, v2
	v_xor_b32_e32 v14, 1, v1
	v_xor_b32_e32 v15, 2, v1
	v_xor_b32_e32 v16, 4, v1
	v_xor_b32_e32 v17, 8, v1
	v_xor_b32_e32 v18, 16, v1
	v_xor_b32_e32 v19, 32, v1
	s_lshl_b32 s79, s77, 14
	s_mov_b32 s80, s79
	v_lshlrev_b32_e32 v44, 4, v178
	v_lshlrev_b32_e32 v45, 6, v178
	s_mov_b32 s81, s0
	s_cmpk_lt_i32 s81, 0x5d00
	s_cselect_b32 s84, s81, s0
	s_cmpk_lt_i32 s84, 0x4000
	s_cselect_b32 s86, s82, s24
	s_cselect_b32 s87, s83, s25
	s_and_b32 s85, s84, 0x3fff
	s_lshl_b32 s85, s85, 12
	s_add_u32 s86, s86, s85
	s_addc_u32 s87, s87, 0
	s_mov_b32 m0, s80
	s_nop 0
	global_load_lds_dwordx4 v45, s[86:87]
	s_add_i32 m0, s80, 0x3f0
	s_nop 0
	global_load_lds_dwordx4 v45, s[86:87] offset:16
	s_add_i32 m0, s80, 0x7e0
	s_nop 0
	global_load_lds_dwordx4 v45, s[86:87] offset:32
	s_add_i32 m0, s80, 0xbd0
	s_nop 0
	global_load_lds_dwordx4 v45, s[86:87] offset:48
	global_load_dword v47, v45, s[86:87]
	global_load_dword v47, v45, s[86:87]
	s_add_i32 s80, s80, 0x1000
	s_sub_i32 s85, s80, s79
	s_and_b32 s85, s85, 0x3fff
	s_add_i32 s80, s79, s85
	s_add_i32 s81, s81, s10
	s_cmpk_lt_i32 s81, 0x5d00
	s_cselect_b32 s84, s81, s0
	s_cmpk_lt_i32 s84, 0x4000
	s_cselect_b32 s86, s82, s24
	s_cselect_b32 s87, s83, s25
	s_and_b32 s85, s84, 0x3fff
	s_lshl_b32 s85, s85, 12
	s_add_u32 s86, s86, s85
	s_addc_u32 s87, s87, 0
	s_mov_b32 m0, s80
	s_nop 0
	global_load_lds_dwordx4 v45, s[86:87]
	s_add_i32 m0, s80, 0x3f0
	s_nop 0
	global_load_lds_dwordx4 v45, s[86:87] offset:16
	s_add_i32 m0, s80, 0x7e0
	s_nop 0
	global_load_lds_dwordx4 v45, s[86:87] offset:32
	s_add_i32 m0, s80, 0xbd0
	s_nop 0
	global_load_lds_dwordx4 v45, s[86:87] offset:48
	global_load_dword v47, v45, s[86:87]
	global_load_dword v47, v45, s[86:87]
	s_add_i32 s80, s80, 0x1000
	s_sub_i32 s85, s80, s79
	s_and_b32 s85, s85, 0x3fff
	s_add_i32 s80, s79, s85
	s_add_i32 s81, s81, s10
	s_cmpk_lt_i32 s81, 0x5d00
	s_cselect_b32 s84, s81, s0
	s_cmpk_lt_i32 s84, 0x4000
	s_cselect_b32 s86, s82, s24
	s_cselect_b32 s87, s83, s25
	s_and_b32 s85, s84, 0x3fff
	s_lshl_b32 s85, s85, 12
	s_add_u32 s86, s86, s85
	s_addc_u32 s87, s87, 0
	s_mov_b32 m0, s80
	s_nop 0
	global_load_lds_dwordx4 v45, s[86:87]
	s_add_i32 m0, s80, 0x3f0
	s_nop 0
	global_load_lds_dwordx4 v45, s[86:87] offset:16
	s_add_i32 m0, s80, 0x7e0
	s_nop 0
	global_load_lds_dwordx4 v45, s[86:87] offset:32
	s_add_i32 m0, s80, 0xbd0
	s_nop 0
	global_load_lds_dwordx4 v45, s[86:87] offset:48
	global_load_dword v47, v45, s[86:87]
	global_load_dword v47, v45, s[86:87]
	s_add_i32 s80, s80, 0x1000
	s_sub_i32 s85, s80, s79
	s_and_b32 s85, s85, 0x3fff
	s_add_i32 s80, s79, s85
	s_add_i32 s81, s81, s10
	s_cmpk_lt_i32 s81, 0x5d00
	s_cselect_b32 s84, s81, s0
	s_cmpk_lt_i32 s84, 0x4000
	s_cselect_b32 s86, s82, s24
	s_cselect_b32 s87, s83, s25
	s_and_b32 s85, s84, 0x3fff
	s_lshl_b32 s85, s85, 12
	s_add_u32 s86, s86, s85
	s_addc_u32 s87, s87, 0
	s_mov_b32 m0, s80
	s_nop 0
	global_load_lds_dwordx4 v45, s[86:87]
	s_add_i32 m0, s80, 0x3f0
	s_nop 0
	global_load_lds_dwordx4 v45, s[86:87] offset:16
	s_add_i32 m0, s80, 0x7e0
	s_nop 0
	global_load_lds_dwordx4 v45, s[86:87] offset:32
	s_add_i32 m0, s80, 0xbd0
	s_nop 0
	global_load_lds_dwordx4 v45, s[86:87] offset:48
	global_load_dword v47, v45, s[86:87]
	global_load_dword v47, v45, s[86:87]
	s_add_i32 s80, s80, 0x1000
	s_sub_i32 s85, s80, s79
	s_and_b32 s85, s85, 0x3fff
	s_add_i32 s80, s79, s85
	s_add_i32 s81, s81, s10
	s_branch .LBB0_463

; __device__ __forceinline__ unsigned fp4_code(float y) { const int q = (int)rintf(y); return (unsigned)q & 15u; }
; __device__ __forceinline__ void cvt_row_fp4(const float* __restrict__ src, unsigned char* __restrict__ T4, float* __restrict__ inv_scale, int e, int lane) {
;     f32x4 v[4]; float am = 0.f;
; #pragma unroll
;     for (int j = 0; j < 4; ++j) { v[j] = *(const f32x4*)(src + (size_t)e * 1024 + 16 * lane + 4 * j);
;         am = fmaxf(am, fmaxf(fmaxf(fabsf(v[j].x), fabsf(v[j].y)), fmaxf(fabsf(v[j].z), fabsf(v[j].w)))); }
; #pragma unroll
;     for (int o = 1; o < 64; o <<= 1) am = fmaxf(am, __shfl_xor(am, o));
;     const float sc = am > 0.f ? 7.f / am : 0.f;
;     unsigned n0 = 0u, n1 = 0u;
; #pragma unroll
;     for (int i = 0; i < 8; ++i) { n0 |= fp4_code(v[i >> 2][i & 3] * sc) << (4 * i); n1 |= fp4_code(v[2 + (i >> 2)][i & 3] * sc) << (4 * i); }
;     const unsigned p0 = (unsigned)__builtin_amdgcn_update_dpp(0, (int)n0, 0xB1, 0xf, 0xf, true), p1 = (unsigned)__builtin_amdgcn_update_dpp(0, (int)n1, 0xB1, 0xf, 0xf, true);
;     if ((lane & 1) == 0) {
.LBB0_462:
	s_add_i32 s0, s0, s10
	s_add_u32 s12, s12, s14
	s_addc_u32 s13, s13, s15
	v_lshl_add_u64 v[10:11], v[10:11], 0, s[16:17]
	s_cmpk_lt_i32 s0, 0x5d00
	v_lshl_add_u64 v[12:13], v[12:13], 0, s[22:23]
	s_cbranch_scc0 .LBB0_472
.LBB0_463:
	s_cmpk_gt_i32 s0, 0x3fff
	s_mov_b64 s[40:41], -1
	s_cbranch_scc0 .LBB0_469
	s_add_i32 s8, s0, 0xffffc000
	s_waitcnt vmcnt(20)
	v_add_u32_e32 v46, s80, v44
	ds_read_b128 v[22:25], v46
	ds_read_b128 v[26:29], v46 offset:1024
	ds_read_b128 v[30:33], v46 offset:2048
	ds_read_b128 v[34:37], v46 offset:3072
	s_lshl_b32 s84, s10, 2
	s_add_i32 s84, s84, s0
	s_cmpk_lt_i32 s84, 0x5d00
	s_cselect_b32 s84, s84, s0
	s_cmpk_lt_i32 s84, 0x4000
	s_cselect_b32 s86, s82, s24
	s_cselect_b32 s87, s83, s25
	s_and_b32 s85, s84, 0x3fff
	s_lshl_b32 s85, s85, 12
	s_add_u32 s86, s86, s85
	s_addc_u32 s87, s87, 0
	v_cmp_lt_i32_e32 vcc, v14, v7
	s_waitcnt lgkmcnt(0)
	s_mov_b32 m0, s80
	s_nop 0
	global_load_lds_dwordx4 v45, s[86:87]
	s_add_i32 m0, s80, 0x3f0
	s_nop 0
	global_load_lds_dwordx4 v45, s[86:87] offset:16
	s_add_i32 m0, s80, 0x7e0
	s_nop 0
	global_load_lds_dwordx4 v45, s[86:87] offset:32
	s_add_i32 m0, s80, 0xbd0
	s_nop 0
	global_load_lds_dwordx4 v45, s[86:87] offset:48
	s_add_i32 s80, s80, 0x1000
	s_sub_i32 s85, s80, s79
	s_and_b32 s85, s85, 0x3fff
	s_add_i32 s80, s79, s85
	v_max_f32_e64 v20, |v25|, |v25|
	v_max_f32_e64 v21, |v24|, |v24|
	v_max_f32_e64 v38, |v29|, |v29|
	v_max_f32_e64 v39, |v28|, |v28|
	v_max_f32_e64 v40, |v33|, |v33|
	v_max_f32_e64 v41, |v32|, |v32|
	v_max_f32_e64 v42, |v37|, |v37|
	v_max_f32_e64 v43, |v36|, |v36|
	v_max_f32_e32 v20, v21, v20
	v_max_f32_e32 v21, v39, v38
	v_max_f32_e32 v38, v41, v40
	v_max_f32_e32 v39, v43, v42
	v_max3_f32 v20, |v22|, |v23|, v20
	v_max3_f32 v21, |v26|, |v27|, v21
	v_cndmask_b32_e32 v2, v1, v14, vcc
	v_max3_f32 v38, |v30|, |v31|, v38
	v_max3_f32 v39, |v34|, |v35|, v39
	v_max3_f32 v20, v20, 0, v21
	v_lshlrev_b32_e32 v2, 2, v2
	v_max3_f32 v20, v20, v38, v39
	ds_bpermute_b32 v2, v2, v20
	v_cmp_lt_i32_e32 vcc, v15, v7
	s_waitcnt lgkmcnt(0)
	v_max_f32_e32 v2, v2, v2
	v_cndmask_b32_e32 v21, v1, v15, vcc
	v_lshlrev_b32_e32 v21, 2, v21
	v_max_f32_e32 v2, v20, v2
	ds_bpermute_b32 v20, v21, v2
	v_cmp_lt_i32_e32 vcc, v16, v7
	s_waitcnt lgkmcnt(0)
	v_max_f32_e32 v20, v20, v20
	v_cndmask_b32_e32 v21, v1, v16, vcc
	v_lshlrev_b32_e32 v21, 2, v21
	v_max_f32_e32 v2, v2, v20
	ds_bpermute_b32 v20, v21, v2
	v_cmp_lt_i32_e32 vcc, v17, v7
	s_waitcnt lgkmcnt(0)
	v_max_f32_e32 v20, v20, v20
	v_cndmask_b32_e32 v21, v1, v17, vcc
	v_lshlrev_b32_e32 v21, 2, v21
	v_max_f32_e32 v2, v2, v20
	ds_bpermute_b32 v20, v21, v2
	v_cmp_lt_i32_e32 vcc, v18, v7
	s_waitcnt lgkmcnt(0)
	v_max_f32_e32 v20, v20, v20
	v_cndmask_b32_e32 v21, v1, v18, vcc
	v_lshlrev_b32_e32 v21, 2, v21
	v_max_f32_e32 v2, v2, v20
	ds_bpermute_b32 v20, v21, v2
	v_cmp_lt_i32_e32 vcc, v19, v7
	s_waitcnt lgkmcnt(0)
	v_max_f32_e32 v20, v20, v20
	v_cndmask_b32_e32 v21, v1, v19, vcc
	v_lshlrev_b32_e32 v21, 2, v21
	v_max_f32_e32 v2, v2, v20
	ds_bpermute_b32 v20, v21, v2
	s_waitcnt lgkmcnt(0)
	v_max_f32_e32 v20, v20, v20
	v_max_f32_e32 v20, v2, v20
	v_div_scale_f32 v2, s[40:41], v20, v20, s1
	v_rcp_f32_e32 v21, v2
	v_div_scale_f32 v38, vcc, s1, v20, s1
	v_fma_f32 v39, -v2, v21, 1.0
	v_fmac_f32_e32 v21, v39, v21
	v_mul_f32_e32 v39, v38, v21
	v_fma_f32 v40, -v2, v39, v38
	v_fmac_f32_e32 v39, v40, v21
	v_fma_f32 v2, -v2, v39, v38
	v_div_fmas_f32 v2, v2, v21, v39
	v_div_fixup_f32 v2, v2, v20, s1
	v_cmp_lt_f32_e32 vcc, 0, v20
	s_nop 1
	v_cndmask_b32_e32 v2, 0, v2, vcc
	v_mul_f32_e32 v21, v22, v2
	v_mul_f32_e32 v22, v30, v2
	v_mul_f32_e32 v23, v23, v2
	v_mul_f32_e32 v30, v31, v2
	v_mul_f32_e32 v31, v32, v2
	v_mul_f32_e32 v25, v25, v2
	v_mul_f32_e32 v32, v33, v2
	v_mul_f32_e32 v26, v26, v2
	v_mul_f32_e32 v33, v34, v2
	v_mul_f32_e32 v27, v27, v2
	v_mul_f32_e32 v34, v35, v2
	v_mul_f32_e32 v24, v24, v2
	v_mul_f32_e32 v28, v28, v2
	v_mul_f32_e32 v35, v36, v2
	v_mul_f32_e32 v29, v29, v2
	v_mul_f32_e32 v2, v37, v2
	v_rndne_f32_e32 v21, v21
	v_rndne_f32_e32 v22, v22
	v_rndne_f32_e32 v23, v23
	v_rndne_f32_e32 v30, v30
	v_rndne_f32_e32 v25, v25
	v_rndne_f32_e32 v32, v32
	v_rndne_f32_e32 v26, v26
	v_rndne_f32_e32 v27, v27
	v_rndne_f32_e32 v34, v34
	v_rndne_f32_e32 v24, v24
	v_rndne_f32_e32 v29, v29
	v_rndne_f32_e32 v2, v2
	v_cvt_i32_f32_e32 v21, v21
	v_cvt_i32_f32_e32 v22, v22
	v_cvt_i32_f32_e32 v23, v23
	v_cvt_i32_f32_e32 v30, v30
	v_cvt_i32_f32_e32 v25, v25
	v_cvt_i32_f32_e32 v32, v32
	v_cvt_i32_f32_sdwa v36, v26 dst_sel:WORD_1 dst_unused:UNUSED_PAD src0_sel:DWORD
	v_cvt_i32_f32_e32 v26, v27
	v_cvt_i32_f32_e32 v27, v34
	v_rndne_f32_e32 v31, v31
	v_rndne_f32_e32 v33, v33
	v_rndne_f32_e32 v28, v28
	v_rndne_f32_e32 v35, v35
	v_cvt_i32_f32_e32 v24, v24
	v_cvt_i32_f32_e32 v29, v29
	v_cvt_i32_f32_e32 v2, v2
	v_cvt_i32_f32_e32 v31, v31
	v_cvt_i32_f32_sdwa v33, v33 dst_sel:WORD_1 dst_unused:UNUSED_PAD src0_sel:DWORD
	v_cvt_i32_f32_sdwa v28, v28 dst_sel:BYTE_3 dst_unused:UNUSED_PAD src0_sel:DWORD
	v_cvt_i32_f32_sdwa v34, v35 dst_sel:BYTE_3 dst_unused:UNUSED_PAD src0_sel:DWORD
	v_and_b32_e32 v21, 15, v21
	v_and_b32_e32 v22, 15, v22
	v_lshlrev_b32_e32 v23, 4, v23
	v_lshlrev_b32_e32 v30, 4, v30
	v_lshlrev_b32_e32 v35, 12, v25
	v_lshlrev_b32_e32 v32, 12, v32
	v_lshlrev_b32_e32 v26, 20, v26
	v_lshlrev_b32_e32 v27, 20, v27
	v_lshlrev_b32_e32 v24, 8, v24
	v_lshlrev_b32_e32 v29, 28, v29
	v_lshlrev_b32_e32 v37, 28, v2
	v_and_or_b32 v25, v23, s3, v21
	v_and_or_b32 v2, v30, s3, v22
	v_and_b32_e32 v22, 0xf000, v35
	v_and_b32_e32 v23, 0xf000, v32
	v_and_b32_e32 v30, 0xf00000, v26
	v_and_b32_e32 v32, 0xf00000, v27
	v_lshlrev_b32_e32 v31, 8, v31
	v_and_or_b32 v26, v28, s34, v29
	v_and_or_b32 v21, v34, s34, v37
	v_and_or_b32 v29, v24, s11, v22
	v_and_or_b32 v27, v36, s19, v30
	v_and_or_b32 v22, v33, s19, v32
	v_and_or_b32 v24, v31, s11, v23
	v_or_b32_e32 v23, v27, v26
	v_or_b32_e32 v28, v22, v21
	v_or3_b32 v23, v23, v25, v29
	v_or3_b32 v30, v28, v2, v24
	s_nop 0
	v_mov_b32_dpp v28, v23 quad_perm:[1,0,3,2] row_mask:0xf bank_mask:0xf bound_ctrl:1
	v_mov_b32_dpp v23, v30 quad_perm:[1,0,3,2] row_mask:0xf bank_mask:0xf bound_ctrl:1
	s_and_saveexec_b64 s[40:41], s[4:5]
	s_cbranch_execz .LBB0_466
; __device__ __forceinline__ void cvt_row_fp4(const float* __restrict__ src, unsigned char* __restrict__ T4, float* __restrict__ inv_scale, int e, int lane) {
;     ...
;     if ((lane & 1) == 0) {
;         v4u o;
;         o.x = spread4(n0) | (spread4(p0) << 4); o.y = spread4(n0 >> 16) | (spread4(p0 >> 16) << 4);
;         o.z = spread4(n1) | (spread4(p1) << 4); o.w = spread4(n1 >> 16) | (spread4(p1 >> 16) << 4);
;         *(v4u*)(T4 + ((size_t)(lane >> 4) * 16384 + e) * 128 + 16 * ((lane & 15) >> 1)) = o;
;     }
;     if (lane == 0) inv_scale[e] = am * (1.f / (7.f * 16.f));
	v_lshl_or_b32 v25, v29, 8, v25
	v_perm_b32 v29, v28, v28, s35
	v_lshlrev_b32_e32 v30, 4, v29
	v_lshl_or_b32 v25, v25, 4, v25
	v_lshl_or_b32 v29, v29, 8, v30
	v_bfi_b32 v30, s42, v25, v29
	v_lshrrev_b32_e32 v25, 8, v26
	v_lshrrev_b32_e32 v26, 16, v28
	v_or_b32_sdwa v25, v25, v27 dst_sel:DWORD dst_unused:UNUSED_PAD src0_sel:DWORD src1_sel:WORD_1
	v_lshlrev_b32_e32 v27, 8, v26
	v_bitop3_b32 v26, v27, s43, v26 bitop3:0xc8
	v_lshlrev_b32_e32 v27, 4, v26
	v_lshl_or_b32 v25, v25, 4, v25
	v_lshl_or_b32 v26, v26, 8, v27
	v_lshl_or_b32 v2, v24, 8, v2
	v_perm_b32 v24, v23, v23, s35
	v_bfi_b32 v31, s42, v25, v26
	v_lshlrev_b32_e32 v25, 4, v24
	v_lshl_or_b32 v2, v2, 4, v2
	v_lshl_or_b32 v24, v24, 8, v25
	v_bfi_b32 v32, s42, v2, v24
	v_lshrrev_b32_e32 v2, 8, v21
	v_lshrrev_b32_e32 v21, 16, v23
	v_or_b32_sdwa v2, v2, v22 dst_sel:DWORD dst_unused:UNUSED_PAD src0_sel:DWORD src1_sel:WORD_1
	v_lshlrev_b32_e32 v22, 8, v21
	v_bitop3_b32 v21, v22, s43, v21 bitop3:0xc8
	v_lshlrev_b32_e32 v22, 4, v21
	v_lshl_or_b32 v2, v2, 4, v2
	v_lshl_or_b32 v21, v21, 8, v22
	v_bfi_b32 v33, s42, v2, v21
	v_add_u32_e32 v2, s8, v6
	v_lshlrev_b64 v[22:23], 7, v[2:3]
	v_lshl_add_u64 v[22:23], v[8:9], 0, v[22:23]
	global_store_dwordx4 v[22:23], v[30:33], off

; __device__ __forceinline__ void cvt_row_i4(const float* __restrict__ src, unsigned char* __restrict__ T4, float* __restrict__ inv_scale, int e, int lane) {
;     f32x4 v[4]; float am = 0.f;
; #pragma unroll
;     for (int j = 0; j < 4; ++j) { v[j] = *(const f32x4*)(src + (size_t)e * 1024 + 16 * lane + 4 * j);
;         am = fmaxf(am, fmaxf(fmaxf(fabsf(v[j].x), fabsf(v[j].y)), fmaxf(fabsf(v[j].z), fabsf(v[j].w)))); }
; #pragma unroll
;     for (int o = 1; o < 64; o <<= 1) am = fmaxf(am, __shfl_xor(am, o));
;     const float sc = am > 0.f ? 7.f / am : 0.f;
;     v2u o;
; #pragma unroll
;     for (int k = 0; k < 2; ++k) { unsigned w = 0u;
; #pragma unroll
;         for (int i = 0; i < 8; ++i) { const int q = (int)rintf(v[2 * k + (i >> 2)][i & 3] * sc); w |= ((unsigned)q & 15u) << (4 * i); }
;         o[k] = w; }
;     *(v2u*)(T4 + ((size_t)(lane >> 4) * 16384 + e) * 128 + 8 * (lane & 15)) = o;
;     if (lane == 0) inv_scale[e] = am * (1.f / 7.f);
.LBB0_469:
	s_and_b64 vcc, exec, s[40:41]
	s_cbranch_vccz .LBB0_462
	s_waitcnt vmcnt(20)
	v_add_u32_e32 v46, s80, v44
	ds_read_b128 v[20:23], v46
	ds_read_b128 v[24:27], v46 offset:1024
	ds_read_b128 v[28:31], v46 offset:2048
	ds_read_b128 v[32:35], v46 offset:3072
	s_lshl_b32 s84, s10, 2
	s_add_i32 s84, s84, s0
	s_cmpk_lt_i32 s84, 0x5d00
	s_cselect_b32 s84, s84, s0
	s_cmpk_lt_i32 s84, 0x4000
	s_cselect_b32 s86, s82, s24
	s_cselect_b32 s87, s83, s25
	s_and_b32 s85, s84, 0x3fff
	s_lshl_b32 s85, s85, 12
	s_add_u32 s86, s86, s85
	s_addc_u32 s87, s87, 0
	v_cmp_lt_i32_e32 vcc, v14, v7
	s_waitcnt lgkmcnt(0)
	s_mov_b32 m0, s80
	s_nop 0
	global_load_lds_dwordx4 v45, s[86:87]
	s_add_i32 m0, s80, 0x3f0
	s_nop 0
	global_load_lds_dwordx4 v45, s[86:87] offset:16
	s_add_i32 m0, s80, 0x7e0
	s_nop 0
	global_load_lds_dwordx4 v45, s[86:87] offset:32
	s_add_i32 m0, s80, 0xbd0
	s_nop 0
	global_load_lds_dwordx4 v45, s[86:87] offset:48
	s_add_i32 s80, s80, 0x1000
	s_sub_i32 s85, s80, s79
	s_and_b32 s85, s85, 0x3fff
	s_add_i32 s80, s79, s85
	v_max_f32_e64 v36, |v23|, |v23|
	v_max_f32_e64 v37, |v22|, |v22|
	v_max_f32_e64 v38, |v27|, |v27|
	v_max_f32_e64 v39, |v26|, |v26|
	v_max_f32_e64 v40, |v31|, |v31|
	v_max_f32_e64 v41, |v30|, |v30|
	v_max_f32_e64 v42, |v35|, |v35|
	v_max_f32_e64 v43, |v34|, |v34|
	v_max_f32_e32 v36, v37, v36
	v_max_f32_e32 v37, v39, v38
	v_max_f32_e32 v38, v41, v40
	v_max_f32_e32 v39, v43, v42
	v_max3_f32 v36, |v20|, |v21|, v36
	v_max3_f32 v37, |v24|, |v25|, v37
	v_cndmask_b32_e32 v2, v1, v14, vcc
	v_max3_f32 v38, |v28|, |v29|, v38
	v_max3_f32 v39, |v32|, |v33|, v39
	v_max3_f32 v36, v36, 0, v37
	v_lshlrev_b32_e32 v2, 2, v2
	v_max3_f32 v36, v36, v38, v39
	ds_bpermute_b32 v2, v2, v36
	v_cmp_lt_i32_e32 vcc, v15, v7
	s_waitcnt lgkmcnt(0)
	v_max_f32_e32 v2, v2, v2
	v_cndmask_b32_e32 v37, v1, v15, vcc
	v_lshlrev_b32_e32 v37, 2, v37
	v_max_f32_e32 v2, v36, v2
	ds_bpermute_b32 v36, v37, v2
	v_cmp_lt_i32_e32 vcc, v16, v7
	s_waitcnt lgkmcnt(0)
	v_max_f32_e32 v36, v36, v36
	v_cndmask_b32_e32 v37, v1, v16, vcc
	v_lshlrev_b32_e32 v37, 2, v37
	v_max_f32_e32 v2, v2, v36
	ds_bpermute_b32 v36, v37, v2
	v_cmp_lt_i32_e32 vcc, v17, v7
	s_waitcnt lgkmcnt(0)
	v_max_f32_e32 v36, v36, v36
	v_cndmask_b32_e32 v37, v1, v17, vcc
	v_lshlrev_b32_e32 v37, 2, v37
	v_max_f32_e32 v2, v2, v36
	ds_bpermute_b32 v36, v37, v2
	v_cmp_lt_i32_e32 vcc, v18, v7
	s_waitcnt lgkmcnt(0)
	v_max_f32_e32 v36, v36, v36
	v_cndmask_b32_e32 v37, v1, v18, vcc
	v_lshlrev_b32_e32 v37, 2, v37
	v_max_f32_e32 v2, v2, v36
	ds_bpermute_b32 v36, v37, v2
	v_cmp_lt_i32_e32 vcc, v19, v7
	s_waitcnt lgkmcnt(0)
	v_max_f32_e32 v36, v36, v36
	v_cndmask_b32_e32 v37, v1, v19, vcc
	v_lshlrev_b32_e32 v37, 2, v37
	v_max_f32_e32 v2, v2, v36
	ds_bpermute_b32 v36, v37, v2
	s_waitcnt lgkmcnt(0)
	v_max_f32_e32 v36, v36, v36
	v_max_f32_e32 v2, v2, v36
	v_div_scale_f32 v36, s[40:41], v2, v2, s1
	v_rcp_f32_e32 v37, v36
	v_div_scale_f32 v38, vcc, s1, v2, s1
	v_fma_f32 v39, -v36, v37, 1.0
	v_fmac_f32_e32 v37, v39, v37
	v_mul_f32_e32 v39, v38, v37
	v_fma_f32 v40, -v36, v39, v38
	v_fmac_f32_e32 v39, v40, v37
	v_fma_f32 v36, -v36, v39, v38
	v_div_fmas_f32 v36, v36, v37, v39
	v_div_fixup_f32 v36, v36, v2, s1
	v_cmp_lt_f32_e32 vcc, 0, v2
	s_nop 1
	v_cndmask_b32_e32 v36, 0, v36, vcc
	v_mul_f32_e32 v20, v20, v36
	v_mul_f32_e32 v21, v21, v36
	v_mul_f32_e32 v22, v22, v36
	v_mul_f32_e32 v28, v28, v36
	v_mul_f32_e32 v29, v29, v36
	v_mul_f32_e32 v30, v30, v36
	v_mul_f32_e32 v23, v23, v36
	v_mul_f32_e32 v27, v27, v36
	v_mul_f32_e32 v31, v31, v36
	v_mul_f32_e32 v35, v35, v36
	v_rndne_f32_e32 v20, v20
	v_rndne_f32_e32 v21, v21
	v_rndne_f32_e32 v22, v22
	v_rndne_f32_e32 v28, v28
	v_rndne_f32_e32 v29, v29
	v_rndne_f32_e32 v30, v30
	v_mul_f32_e32 v24, v24, v36
	v_mul_f32_e32 v25, v25, v36
	v_mul_f32_e32 v32, v32, v36
	v_mul_f32_e32 v33, v33, v36
	v_rndne_f32_e32 v23, v23
	v_rndne_f32_e32 v27, v27
	v_rndne_f32_e32 v31, v31
	v_rndne_f32_e32 v35, v35
	v_cvt_i32_f32_e32 v20, v20
	v_cvt_i32_f32_e32 v21, v21
	v_cvt_i32_f32_e32 v22, v22
	v_cvt_i32_f32_e32 v28, v28
	v_cvt_i32_f32_e32 v29, v29
	v_cvt_i32_f32_e32 v30, v30
	v_mul_f32_e32 v26, v26, v36
	v_mul_f32_e32 v34, v34, v36
	v_rndne_f32_e32 v24, v24
	v_rndne_f32_e32 v25, v25
	v_rndne_f32_e32 v32, v32
	v_rndne_f32_e32 v33, v33
	v_cvt_i32_f32_e32 v23, v23
	v_cvt_i32_f32_e32 v27, v27
	v_cvt_i32_f32_e32 v31, v31
	v_cvt_i32_f32_e32 v35, v35
	v_rndne_f32_e32 v26, v26
	v_rndne_f32_e32 v34, v34
	v_cvt_i32_f32_sdwa v24, v24 dst_sel:WORD_1 dst_unused:UNUSED_PAD src0_sel:DWORD
	v_cvt_i32_f32_e32 v25, v25
	v_cvt_i32_f32_sdwa v32, v32 dst_sel:WORD_1 dst_unused:UNUSED_PAD src0_sel:DWORD
	v_cvt_i32_f32_e32 v33, v33
	v_cvt_i32_f32_sdwa v26, v26 dst_sel:BYTE_3 dst_unused:UNUSED_PAD src0_sel:DWORD
	v_cvt_i32_f32_sdwa v34, v34 dst_sel:BYTE_3 dst_unused:UNUSED_PAD src0_sel:DWORD
	v_and_b32_e32 v20, 15, v20
	v_lshlrev_b32_e32 v21, 4, v21
	v_lshlrev_b32_e32 v22, 8, v22
	v_and_b32_e32 v28, 15, v28
	v_lshlrev_b32_e32 v29, 4, v29
	v_lshlrev_b32_e32 v30, 8, v30
	v_lshlrev_b32_e32 v23, 12, v23
	v_lshlrev_b32_e32 v31, 12, v31
	v_and_b32_e32 v21, 0xf0, v21
	v_and_b32_e32 v22, 0xf00, v22
	v_lshl_or_b32 v20, v27, 28, v20
	v_and_b32_e32 v27, 0xf0, v29
	v_and_b32_e32 v29, 0xf00, v30
	v_lshl_or_b32 v28, v35, 28, v28
	v_and_b32_e32 v24, 0xf0000, v24
	v_lshlrev_b32_e32 v25, 20, v25
	v_and_b32_e32 v32, 0xf0000, v32
	v_lshlrev_b32_e32 v33, 20, v33
	v_and_b32_e32 v23, 0xf000, v23
	v_and_b32_e32 v30, 0xf000, v31
	v_or3_b32 v20, v20, v21, v22
	v_or3_b32 v21, v28, v27, v29
	v_and_b32_e32 v26, 0xf000000, v26
	v_and_b32_e32 v34, 0xf000000, v34
	v_and_b32_e32 v25, 0xf00000, v25
	v_and_b32_e32 v31, 0xf00000, v33
	v_or3_b32 v20, v20, v23, v24
	v_or3_b32 v21, v21, v30, v32
	v_or3_b32 v20, v20, v25, v26
	v_or3_b32 v21, v21, v31, v34
	global_store_dwordx2 v[10:11], v[20:21], off
	s_and_saveexec_b64 s[40:41], s[6:7]
	s_cbranch_execz .LBB0_461
	v_mul_f32_e32 v2, 0x3e124925, v2
	global_store_dword v3, v2, s[12:13]
	s_branch .LBB0_461

; __global__ void __launch_bounds__(NTHR, 2) mega(Args args) {
;     ...
;         {
;             const int nextra = 288 > G ? 288 - G : 0, nslack = G - nextra;
;             if ((int)blockIdx.x >= nextra && rep == 0)
;                 for (int e = 2 * 16384 - CVT_LATE + ((int)blockIdx.x - nextra) * NWAVES + wave; e < 2 * 16384; e += nslack * NWAVES) peer::cvt_row_fp4(pv, VT8, SVs, e - 16384, lane);
;         }
.LBB0_537:
	s_sub_i32 s0, 0x120, s18
	s_cmpk_lt_i32 s18, 0x120
	s_cselect_b32 s0, s0, 0
	s_cmp_lt_i32 s2, s0
	s_cselect_b64 s[4:5], -1, 0
	s_sub_i32 s1, s2, s0
	s_lshl_b32 s1, s1, 3
	s_add_i32 s1, s77, s1
	s_add_i32 s3, s1, 0x5d00
	s_cmpk_gt_i32 s3, 0x7fff
	s_cselect_b64 s[6:7], -1, 0
	s_or_b64 s[4:5], s[4:5], s[6:7]
	s_andn2_b64 vcc, exec, s[4:5]
	s_cbranch_vccz .LBB0_544
	v_and_b32_e32 v1, 1, v0
	v_cmp_eq_u32_e64 s[4:5], 0, v1
	v_mbcnt_lo_u32_b32 v1, -1, 0
	v_mbcnt_hi_u32_b32 v2, -1, v1
	v_and_b32_e32 v1, 64, v2
	v_add_u32_e32 v3, 64, v1
	v_xor_b32_e32 v1, 1, v2
	v_cmp_lt_i32_e32 vcc, v1, v3
	v_xor_b32_e32 v4, 2, v2
	s_add_i32 s3, s2, s18
	v_cndmask_b32_e32 v1, v2, v1, vcc
	v_cmp_lt_i32_e32 vcc, v4, v3
	s_lshl_b32 s3, s3, 3
	s_max_i32 s10, s18, 0x120
	v_cndmask_b32_e32 v4, v2, v4, vcc
	v_lshlrev_b32_e32 v8, 2, v4
	v_xor_b32_e32 v4, 4, v2
	v_cmp_lt_i32_e32 vcc, v4, v3
	s_add_i32 s3, s77, s3
	s_lshl_b32 s10, s10, 3
	v_cndmask_b32_e32 v4, v2, v4, vcc
	v_lshlrev_b32_e32 v9, 2, v4
	v_xor_b32_e32 v4, 8, v2
	v_cmp_lt_i32_e32 vcc, v4, v3
	s_add_i32 s16, s1, 0x1d00
	s_sub_i32 s0, s18, s0
	v_cndmask_b32_e32 v4, v2, v4, vcc
	v_lshlrev_b32_e32 v10, 2, v4
	v_xor_b32_e32 v4, 16, v2
	v_cmp_lt_i32_e32 vcc, v4, v3
	s_sub_i32 s3, s3, s10
	s_ashr_i32 s17, s16, 31
	v_cndmask_b32_e32 v4, v2, v4, vcc
	s_lshl_b32 s0, s0, 3
	v_lshlrev_b32_e32 v11, 2, v4
	v_xor_b32_e32 v4, 32, v2
	s_addk_i32 s3, 0x5d00
	s_lshl_b64 s[10:11], s[16:17], 2
	v_cmp_lt_i32_e32 vcc, v4, v3
	s_add_u32 s1, s30, s10
	s_addc_u32 s11, s31, s11
	v_cndmask_b32_e32 v2, v2, v4, vcc
	v_lshlrev_b32_e32 v12, 2, v2
	s_add_u32 s10, s1, 0x3100000
	v_lshlrev_b32_e32 v2, 17, v0
	s_addc_u32 s11, s11, 0
	v_and_b32_e32 v2, 0x600000, v2
	v_mov_b32_e32 v3, 0
	s_lshl_b64 s[14:15], s[16:17], 7
	v_lshlrev_b32_e32 v6, 3, v0
	v_lshl_add_u64 v[4:5], v[2:3], 0, s[14:15]
	s_movk_i32 s14, 0x70
	v_and_or_b32 v4, v6, s14, v4
	s_ashr_i32 s1, s0, 31
	v_lshl_add_u64 v[4:5], s[30:31], 0, v[4:5]
	s_mov_b64 s[14:15], 0x2000000
	s_lshl_b64 s[12:13], s[0:1], 2
	v_lshl_add_u64 v[4:5], v[4:5], 0, s[14:15]
	s_lshl_b64 s[14:15], s[0:1], 7
	s_lshl_b64 s[16:17], s[16:17], 12
	s_add_u32 s16, s24, s16
	v_lshlrev_b32_e32 v2, 6, v178
	s_addc_u32 s17, s25, s17
	v_lshl_add_u64 v[6:7], s[16:17], 0, v[2:3]
	v_cmp_eq_u32_e64 s[6:7], 0, v178
	v_lshlrev_b32_e32 v1, 2, v1
	v_lshl_add_u64 v[6:7], v[6:7], 0, 32
	s_lshl_b64 s[16:17], s[0:1], 12
	s_mov_b32 s1, 0x40e00000
	s_movk_i32 s19, 0xf0
	s_movk_i32 s24, 0xf00
	s_mov_b32 s25, 0xf0000
	s_mov_b32 s34, 0xf000000
	s_mov_b32 s35, 0xc050c00
	s_mov_b32 s40, 0xf0f0f0f
	s_mov_b32 s41, 0xff00ff
	s_branch .LBB0_540
